# lane-swap S5 loops: steady-state chunks 17..268 run in a trimmed body (incrementing row pointer, unmasked u, load issued at iteration end)
# speedup vs baseline: 1.0086x; 1.0049x over previous
; #define LAS __attribute__((address_space(3)))
; DI unsigned pk2(float lo, float hi) { f32x2 v = {lo, hi}; bf16x2_t b = __builtin_convertvector(v, bf16x2_t); return __builtin_bit_cast(unsigned, b); }
; #define MFMA16(a, b, c) __builtin_amdgcn_mfma_f32_16x16x32_bf16((a), (b), (c), 0, 0, 0)
; #define S5_CB() asm volatile("" ::: "memory")
; DI void s5_phase(const KArgs& a, int zz, int o, const bf16_t* H, bf16_t* YF, bf16_t* YB, LAS unsigned char* lds, int G, int bid, int wave, int lane) {
;     ...
;         auto iter = [&](const int ci, const bool do_c) __attribute__((always_inline)) {
;             const size_t row0 = chunk_row(ci);
;             const u32x4 u3 = loadu(ci + 3);
;             f32x2 bu[16];
; #pragma unroll
;             for (int s = 0; s < 16; ++s) { const int tt = DIRC ? 15 - s : s; bu[s] = *(const LAS f32x2*)(BU + tt * 132 + 2 * lane); }
;             bf16x8 Ax[4];
;             if (do_c) {
; #pragma unroll
;                 for (int kb = 0; kb < 4; ++kb) Ax[kb] = *(const LAS bf16x8*)(XS + fr * 68 + kb * 16 + fq * 4); }
;             S5_CB();
;             stageA(u1);
;             S5_CB();
; #pragma unroll
;             for (int s = 0; s < 16; ++s) { const int tt = DIRC ? 15 - s : s;
;                 const float nr = __builtin_fmaf(abr, xr, __builtin_fmaf(nabi, xi, bu[s][0])); const float ni = __builtin_fmaf(abr, xi, __builtin_fmaf(abi, xr, bu[s][1])); xr = nr; xi = ni;
;                 XS[tt * 68 + lane] = pk2(xr, xi); }
;             if (do_c) {
;                 f32x4 ya = (f32x4){0.f, 0.f, 0.f, 0.f};
; #pragma unroll
;                 for (int kb = 0; kb < 4; ++kb) ya = MFMA16(Cb[kb], Ax[kb], ya);
;                 u32x2 w; w.x = pk2(ya[0], ya[1]); w.y = pk2(ya[2], ya[3]); *(u32x2*)(Y + (rowprev + fr) * D + g * 16 + fq * 4) = w; }
;             S5_CB();
;             rowprev = row0; u1 = u2; u2 = u3;
;         };
;         iter(0, false);
;         for (int ci = 1; ci < 272; ++ci) iter(ci, true);
.LBB0_414:
	s_waitcnt vmcnt(1)
	v_cndmask_b32_e64 v173, 0, v52, s[38:39]
	v_sub_co_u32_e64 v52, s[26:27], s25, 16
	s_and_b64 s[30:31], s[26:27], exec
	v_readfirstlane_b32 s30, v52
	s_cselect_b32 s30, s25, s30
	s_cselect_b32 s31, 15, 0xff
	s_sub_i32 s30, s31, s30
	s_lshl_b32 s30, s30, 4
	s_ashr_i32 s31, s30, 31
	s_and_b64 s[26:27], s[26:27], exec
	s_cselect_b32 s26, s23, s58
	s_cselect_b32 s27, s24, s59
	s_add_u32 s26, s26, s30
	s_addc_u32 s27, s27, s31
	s_min_i32 s36, s25, 0x10c
	s_cmp_lt_u32 s25, 13
	s_cselect_b64 s[30:31], -1, 0
	s_and_b64 s[34:35], s[30:31], exec
	s_cselect_b32 s34, -3, 13
	s_cselect_b32 s35, 15, 0xff
	s_sub_i32 s34, s34, s36
	s_add_i32 s34, s34, s35
	s_lshl_b32 s34, s34, 4
	s_ashr_i32 s35, s34, 31
	s_and_b64 s[30:31], s[30:31], exec
	s_cselect_b32 s31, s23, s58
	s_cselect_b32 s30, s24, s59
	s_add_u32 s31, s31, s34
	s_addc_u32 s30, s30, s35
	v_cndmask_b32_e64 v172, 0, v53, s[38:39]
	v_mov_b32_e32 v53, s30
	v_or_b32_e32 v52, s31, v104
	v_lshlrev_b64 v[52:53], 11, v[52:53]
	v_lshl_add_u64 v[52:53], v[126:127], 0, v[52:53]
	v_add_u32_e32 v148, v134, v107
	v_cndmask_b32_e64 v170, 0, v55, s[38:39]
	v_cndmask_b32_e64 v171, 0, v54, s[38:39]
	global_load_dwordx4 v[52:55], v[52:53], off
	ds_read_b128 v[56:59], v148 offset:8448
	ds_read_b128 v[60:63], v148 offset:8512
	ds_read_b128 v[64:67], v148 offset:8576
	ds_read_b128 v[68:71], v148 offset:8640
	s_waitcnt lgkmcnt(0)
	v_mfma_f32_16x16x32_bf16 v[56:59], v[32:35], v[56:59], 0
	v_mfma_f32_16x16x32_bf16 v[56:59], v[36:39], v[60:63], v[56:59]
	v_mfma_f32_16x16x32_bf16 v[56:59], v[40:43], v[64:67], v[56:59]
	v_mfma_f32_16x16x32_bf16 v[56:59], v[44:47], v[68:71], v[56:59]
	v_fma_f32 v60, -v125, v133, v241
	v_fma_f32 v61, v125, v132, v245
	v_fmac_f32_e32 v60, v122, v132
	v_fmac_f32_e32 v61, v122, v133
	v_fma_f32 v63, -v125, v61, v240
	v_fmac_f32_e32 v244, v125, v60
	v_fmac_f32_e32 v63, v122, v60
	v_fmac_f32_e32 v244, v122, v61
	v_cvt_pk_bf16_f32 v62, v60, v61
	v_cvt_pk_bf16_f32 v60, v63, v244
	ds_write2_b32 v162, v60, v62 offset0:120 offset1:188
	v_fma_f32 v60, -v125, v244, v239
	v_fma_f32 v61, v125, v63, v243
	v_fmac_f32_e32 v60, v122, v63
	v_fmac_f32_e32 v61, v122, v244
	v_fma_f32 v63, -v125, v61, v238
	v_fmac_f32_e32 v242, v125, v60
	v_fmac_f32_e32 v63, v122, v60
	v_fmac_f32_e32 v242, v122, v61
	v_cvt_pk_bf16_f32 v62, v60, v61
	v_cvt_pk_bf16_f32 v60, v63, v242
	ds_write2_b32 v163, v60, v62 offset0:112 offset1:180
	v_fma_f32 v60, -v125, v242, v233
	v_fma_f32 v61, v125, v63, v237
	v_fmac_f32_e32 v60, v122, v63
	v_fmac_f32_e32 v61, v122, v242
	v_fma_f32 v63, -v125, v61, v232
	v_fmac_f32_e32 v236, v125, v60
	v_fmac_f32_e32 v63, v122, v60
	v_fmac_f32_e32 v236, v122, v61
	v_cvt_pk_bf16_f32 v62, v60, v61
	v_cvt_pk_bf16_f32 v60, v63, v236
	ds_write2_b32 v164, v60, v62 offset0:104 offset1:172
	v_fma_f32 v60, -v125, v236, v231
	v_fma_f32 v61, v125, v63, v235
	v_fmac_f32_e32 v60, v122, v63
	v_fmac_f32_e32 v61, v122, v236
	v_fma_f32 v63, -v125, v61, v230
	v_fmac_f32_e32 v234, v125, v60
	v_fmac_f32_e32 v63, v122, v60
	v_fmac_f32_e32 v234, v122, v61
	v_cvt_pk_bf16_f32 v62, v60, v61
	v_cvt_pk_bf16_f32 v60, v63, v234
	ds_write2_b32 v165, v60, v62 offset0:96 offset1:164
	v_fma_f32 v60, -v125, v234, v225
	v_fma_f32 v61, v125, v63, v229
	v_fmac_f32_e32 v60, v122, v63
	v_fmac_f32_e32 v61, v122, v234
	v_fma_f32 v63, -v125, v61, v224
	v_fmac_f32_e32 v228, v125, v60
	v_fmac_f32_e32 v63, v122, v60
	v_fmac_f32_e32 v228, v122, v61
	v_cvt_pk_bf16_f32 v62, v60, v61
	v_cvt_pk_bf16_f32 v60, v63, v228
	ds_write2_b32 v166, v60, v62 offset0:88 offset1:156
	v_fma_f32 v60, -v125, v228, v223
	v_fma_f32 v61, v125, v63, v227
	v_fmac_f32_e32 v60, v122, v63
	v_fmac_f32_e32 v61, v122, v228
	v_fma_f32 v63, -v125, v61, v222
	v_fmac_f32_e32 v226, v125, v60
	v_fmac_f32_e32 v63, v122, v60
	v_fmac_f32_e32 v226, v122, v61
	v_cvt_pk_bf16_f32 v62, v60, v61
	v_cvt_pk_bf16_f32 v60, v63, v226
	ds_write2_b32 v167, v60, v62 offset0:80 offset1:148
	v_fma_f32 v60, -v125, v226, v217
	v_fma_f32 v61, v125, v63, v221
	v_fmac_f32_e32 v60, v122, v63
	v_fmac_f32_e32 v61, v122, v226
	v_fma_f32 v63, -v125, v61, v216
	v_fmac_f32_e32 v220, v125, v60
	v_fmac_f32_e32 v63, v122, v60
	v_fmac_f32_e32 v220, v122, v61
	v_cvt_pk_bf16_f32 v62, v60, v61
	v_cvt_pk_bf16_f32 v60, v63, v220
	ds_write2_b32 v168, v60, v62 offset0:72 offset1:140
	v_fma_f32 v60, -v125, v220, v215
	v_fma_f32 v61, v125, v63, v219
	v_fmac_f32_e32 v60, v122, v63
	v_fmac_f32_e32 v61, v122, v220
	v_fma_f32 v63, -v125, v61, v214
	v_fmac_f32_e32 v218, v125, v60
	v_fmac_f32_e32 v63, v122, v60
	v_fmac_f32_e32 v218, v122, v61
	v_cvt_pk_bf16_f32 v62, v60, v61
	v_cvt_pk_bf16_f32 v60, v63, v218
	ds_write2_b32 v169, v60, v62 offset0:64 offset1:132
	v_mov_b32_e32 v132, v63
	v_mov_b32_e32 v133, v218
	v_mfma_f32_16x16x32_bf16 v[214:217], v[48:51], v[178:181], 0
	v_mfma_f32_16x16x32_bf16 v[222:225], v[48:51], v[186:189], 0
	v_mfma_f32_16x16x32_bf16 v[230:233], v[48:51], v[194:197], 0
	v_mfma_f32_16x16x32_bf16 v[238:241], v[48:51], v[202:205], 0
	v_mfma_f32_16x16x32_bf16 v[218:221], v[48:51], v[182:185], 0
	v_mfma_f32_16x16x32_bf16 v[226:229], v[48:51], v[190:193], 0
	v_mfma_f32_16x16x32_bf16 v[234:237], v[48:51], v[198:201], 0
	v_mfma_f32_16x16x32_bf16 v[242:245], v[48:51], v[206:209], 0
	v_cvt_pk_bf16_f32 v56, v56, v57
	v_cvt_pk_bf16_f32 v57, v58, v59
	v_lshl_add_u64 v[62:63], s[0:1], 0, v[104:105]
	v_lshlrev_b64 v[62:63], 11, v[62:63]
	v_lshl_add_u64 v[62:63], v[128:129], 0, v[62:63]
	global_store_dwordx2 v[62:63], v[56:57], off
	v_permlane32_swap_b32_e32 v214, v230
	v_permlane32_swap_b32_e32 v222, v238
	v_permlane32_swap_b32_e32 v215, v231
	v_permlane32_swap_b32_e32 v223, v239
	v_permlane32_swap_b32_e32 v216, v232
	v_permlane32_swap_b32_e32 v224, v240
	v_permlane32_swap_b32_e32 v217, v233
	v_permlane32_swap_b32_e32 v225, v241
	v_permlane16_swap_b32_e32 v214, v222
	v_permlane16_swap_b32_e32 v230, v238
	v_permlane16_swap_b32_e32 v215, v223
	v_permlane16_swap_b32_e32 v231, v239
	v_permlane16_swap_b32_e32 v216, v224
	v_permlane16_swap_b32_e32 v232, v240
	v_permlane16_swap_b32_e32 v217, v225
	v_permlane16_swap_b32_e32 v233, v241
	v_permlane32_swap_b32_e32 v218, v234
	v_permlane32_swap_b32_e32 v226, v242
	v_permlane32_swap_b32_e32 v219, v235
	v_permlane32_swap_b32_e32 v227, v243
	v_permlane32_swap_b32_e32 v220, v236
	v_permlane32_swap_b32_e32 v228, v244
	v_permlane32_swap_b32_e32 v221, v237
	v_permlane32_swap_b32_e32 v229, v245
	v_permlane16_swap_b32_e32 v218, v226
	v_permlane16_swap_b32_e32 v234, v242
	v_permlane16_swap_b32_e32 v219, v227
	v_permlane16_swap_b32_e32 v235, v243
	v_permlane16_swap_b32_e32 v220, v228
	v_permlane16_swap_b32_e32 v236, v244
	v_permlane16_swap_b32_e32 v221, v229
	v_permlane16_swap_b32_e32 v237, v245
	s_mov_b64 s[0:1], s[26:27]
	v_mov_b32_e32 v48, v173
	v_mov_b32_e32 v49, v172
	v_mov_b32_e32 v50, v171
	v_mov_b32_e32 v51, v170
	s_add_i32 s25, s25, 1
	s_cmp_eq_u32 s25, 17
	s_cbranch_scc1 .Ls5f_bwd_entry
; #define LAS __attribute__((address_space(3)))
; DI unsigned pk2(float lo, float hi) { f32x2 v = {lo, hi}; bf16x2_t b = __builtin_convertvector(v, bf16x2_t); return __builtin_bit_cast(unsigned, b); }
; #define LDS_WAIT() asm volatile("s_waitcnt lgkmcnt(0)" ::: "memory")
; #define MFMA16(a, b, c) __builtin_amdgcn_mfma_f32_16x16x32_bf16((a), (b), (c), 0, 0, 0)
; DI void s5_phase(const KArgs& a, int zz, int o, const bf16_t* H, bf16_t* YF, bf16_t* YB, LAS unsigned char* lds, int G, int bid, int wave, int lane) {
;     ...
;         for (int ci = 1; ci < 272; ++ci) iter(ci, true);
;         {
;             f32x4 ya = (f32x4){0.f, 0.f, 0.f, 0.f};
; #pragma unroll
;             for (int kb = 0; kb < 4; ++kb) { const bf16x8 Ax = *(const LAS bf16x8*)(XS + fr * 68 + kb * 16 + fq * 4); ya = MFMA16(Cb[kb], Ax, ya); }
;             u32x2 w; w.x = pk2(ya[0], ya[1]); w.y = pk2(ya[2], ya[3]); *(u32x2*)(Y + (rowprev + fr) * D + g * 16 + fq * 4) = w;
;         }
;         LDS_WAIT();
;         };
;         if (dir) run_dir(std::true_type{}); else run_dir(std::false_type{});
	s_cmpk_lg_i32 s25, 0x110
	s_cbranch_scc1 .LBB0_414
	s_waitcnt vmcnt(0)
	ds_read_b128 v[48:51], v148 offset:8448
	ds_read_b128 v[52:55], v148 offset:8512
	s_mov_b32 s36, s12
	s_waitcnt lgkmcnt(1)
	v_mfma_f32_16x16x32_bf16 v[48:51], v[32:35], v[48:51], 0
	s_waitcnt lgkmcnt(0)
	v_mfma_f32_16x16x32_bf16 v[48:51], v[36:39], v[52:55], v[48:51]
	ds_read_b128 v[52:55], v148 offset:8576
	s_waitcnt lgkmcnt(0)
	v_mfma_f32_16x16x32_bf16 v[48:51], v[40:43], v[52:55], v[48:51]
	ds_read_b128 v[52:55], v148 offset:8640
	v_lshlrev_b32_e32 v148, 1, v106
	s_waitcnt lgkmcnt(0)
	v_mfma_f32_16x16x32_bf16 v[48:51], v[44:47], v[52:55], v[48:51]
	s_nop 7
	v_cvt_pk_bf16_f32 v48, v48, v49
	v_cvt_pk_bf16_f32 v49, v50, v51
	v_mov_b32_e32 v51, s27
	v_or_b32_e32 v50, s26, v104
	v_lshlrev_b64 v[50:51], 11, v[50:51]
	v_lshl_add_u64 v[50:51], s[6:7], 0, v[50:51]
	v_lshl_add_u64 v[50:51], s[52:53], 1, v[50:51]
	v_lshl_add_u64 v[50:51], v[50:51], 0, v[148:149]
	global_store_dwordx2 v[50:51], v[48:49], off
	s_waitcnt lgkmcnt(0)
	s_branch .LBB0_394
.Ls5f_bwd_entry:
	s_add_u32 s98, s58, 0xfb0
	s_addc_u32 s99, s59, 0
	s_mov_b32 s100, 0x20000
	s_mov_b32 s101, 0
	s_lshl_b64 s[98:99], s[98:99], 11
	v_lshlrev_b64 v[56:57], 11, v[104:105]
	v_lshl_add_u64 v[246:247], v[126:127], 0, v[56:57]
	v_lshl_add_u64 v[248:249], v[128:129], 0, v[56:57]
	v_lshl_add_u64 v[248:249], v[248:249], 0, s[100:101]
	s_mov_b32 s100, 17
; #define LAS __attribute__((address_space(3)))
; DI unsigned pk2(float lo, float hi) { f32x2 v = {lo, hi}; bf16x2_t b = __builtin_convertvector(v, bf16x2_t); return __builtin_bit_cast(unsigned, b); }
; #define MFMA16(a, b, c) __builtin_amdgcn_mfma_f32_16x16x32_bf16((a), (b), (c), 0, 0, 0)
; #define S5_CB() asm volatile("" ::: "memory")
; DI void s5_phase(const KArgs& a, int zz, int o, const bf16_t* H, bf16_t* YF, bf16_t* YB, LAS unsigned char* lds, int G, int bid, int wave, int lane) {
;     ...
;         auto iter = [&](const int ci, const bool do_c) __attribute__((always_inline)) {
;             const size_t row0 = chunk_row(ci);
;             const u32x4 u3 = loadu(ci + 3);
;             f32x2 bu[16];
; #pragma unroll
;             for (int s = 0; s < 16; ++s) { const int tt = DIRC ? 15 - s : s; bu[s] = *(const LAS f32x2*)(BU + tt * 132 + 2 * lane); }
;             bf16x8 Ax[4];
;             if (do_c) {
; #pragma unroll
;                 for (int kb = 0; kb < 4; ++kb) Ax[kb] = *(const LAS bf16x8*)(XS + fr * 68 + kb * 16 + fq * 4); }
;             S5_CB();
;             stageA(u1);
;             S5_CB();
; #pragma unroll
;             for (int s = 0; s < 16; ++s) { const int tt = DIRC ? 15 - s : s;
;                 const float nr = __builtin_fmaf(abr, xr, __builtin_fmaf(nabi, xi, bu[s][0])); const float ni = __builtin_fmaf(abr, xi, __builtin_fmaf(abi, xr, bu[s][1])); xr = nr; xi = ni;
;                 XS[tt * 68 + lane] = pk2(xr, xi); }
;             if (do_c) {
;                 f32x4 ya = (f32x4){0.f, 0.f, 0.f, 0.f};
; #pragma unroll
;                 for (int kb = 0; kb < 4; ++kb) ya = MFMA16(Cb[kb], Ax[kb], ya);
;                 u32x2 w; w.x = pk2(ya[0], ya[1]); w.y = pk2(ya[2], ya[3]); *(u32x2*)(Y + (rowprev + fr) * D + g * 16 + fq * 4) = w; }
;             S5_CB();
;             rowprev = row0; u1 = u2; u2 = u3;
;         };
;         iter(0, false);
;         for (int ci = 1; ci < 272; ++ci) iter(ci, true);
.Ls5f_bwd_loop:
	ds_read_b128 v[56:59], v148 offset:8448
	ds_read_b128 v[60:63], v148 offset:8512
	ds_read_b128 v[64:67], v148 offset:8576
	ds_read_b128 v[68:71], v148 offset:8640
	s_waitcnt lgkmcnt(0)
	v_mfma_f32_16x16x32_bf16 v[56:59], v[32:35], v[56:59], 0
	v_mfma_f32_16x16x32_bf16 v[56:59], v[36:39], v[60:63], v[56:59]
	v_mfma_f32_16x16x32_bf16 v[56:59], v[40:43], v[64:67], v[56:59]
	v_mfma_f32_16x16x32_bf16 v[56:59], v[44:47], v[68:71], v[56:59]
	v_fma_f32 v60, -v125, v133, v241
	v_fma_f32 v61, v125, v132, v245
	v_fmac_f32_e32 v60, v122, v132
	v_fmac_f32_e32 v61, v122, v133
	v_fma_f32 v63, -v125, v61, v240
	v_fmac_f32_e32 v244, v125, v60
	v_fmac_f32_e32 v63, v122, v60
	v_fmac_f32_e32 v244, v122, v61
	v_cvt_pk_bf16_f32 v62, v60, v61
	v_cvt_pk_bf16_f32 v60, v63, v244
	ds_write2_b32 v162, v60, v62 offset0:120 offset1:188
	v_fma_f32 v60, -v125, v244, v239
	v_fma_f32 v61, v125, v63, v243
	v_fmac_f32_e32 v60, v122, v63
	v_fmac_f32_e32 v61, v122, v244
	v_fma_f32 v63, -v125, v61, v238
	v_fmac_f32_e32 v242, v125, v60
	v_fmac_f32_e32 v63, v122, v60
	v_fmac_f32_e32 v242, v122, v61
	v_cvt_pk_bf16_f32 v62, v60, v61
	v_cvt_pk_bf16_f32 v60, v63, v242
	ds_write2_b32 v163, v60, v62 offset0:112 offset1:180
	v_fma_f32 v60, -v125, v242, v233
	v_fma_f32 v61, v125, v63, v237
	v_fmac_f32_e32 v60, v122, v63
	v_fmac_f32_e32 v61, v122, v242
	v_fma_f32 v63, -v125, v61, v232
	v_fmac_f32_e32 v236, v125, v60
	v_fmac_f32_e32 v63, v122, v60
	v_fmac_f32_e32 v236, v122, v61
	v_cvt_pk_bf16_f32 v62, v60, v61
	v_cvt_pk_bf16_f32 v60, v63, v236
	ds_write2_b32 v164, v60, v62 offset0:104 offset1:172
	v_fma_f32 v60, -v125, v236, v231
	v_fma_f32 v61, v125, v63, v235
	v_fmac_f32_e32 v60, v122, v63
	v_fmac_f32_e32 v61, v122, v236
	v_fma_f32 v63, -v125, v61, v230
	v_fmac_f32_e32 v234, v125, v60
	v_fmac_f32_e32 v63, v122, v60
	v_fmac_f32_e32 v234, v122, v61
	v_cvt_pk_bf16_f32 v62, v60, v61
	v_cvt_pk_bf16_f32 v60, v63, v234
	ds_write2_b32 v165, v60, v62 offset0:96 offset1:164
	v_fma_f32 v60, -v125, v234, v225
	v_fma_f32 v61, v125, v63, v229
	v_fmac_f32_e32 v60, v122, v63
	v_fmac_f32_e32 v61, v122, v234
	v_fma_f32 v63, -v125, v61, v224
	v_fmac_f32_e32 v228, v125, v60
	v_fmac_f32_e32 v63, v122, v60
	v_fmac_f32_e32 v228, v122, v61
	v_cvt_pk_bf16_f32 v62, v60, v61
	v_cvt_pk_bf16_f32 v60, v63, v228
	ds_write2_b32 v166, v60, v62 offset0:88 offset1:156
	v_fma_f32 v60, -v125, v228, v223
	v_fma_f32 v61, v125, v63, v227
	v_fmac_f32_e32 v60, v122, v63
	v_fmac_f32_e32 v61, v122, v228
	v_fma_f32 v63, -v125, v61, v222
	v_fmac_f32_e32 v226, v125, v60
	v_fmac_f32_e32 v63, v122, v60
	v_fmac_f32_e32 v226, v122, v61
	v_cvt_pk_bf16_f32 v62, v60, v61
	v_cvt_pk_bf16_f32 v60, v63, v226
	ds_write2_b32 v167, v60, v62 offset0:80 offset1:148
	v_fma_f32 v60, -v125, v226, v217
	v_fma_f32 v61, v125, v63, v221
	v_fmac_f32_e32 v60, v122, v63
	v_fmac_f32_e32 v61, v122, v226
	v_fma_f32 v63, -v125, v61, v216
	v_fmac_f32_e32 v220, v125, v60
	v_fmac_f32_e32 v63, v122, v60
	v_fmac_f32_e32 v220, v122, v61
	v_cvt_pk_bf16_f32 v62, v60, v61
	v_cvt_pk_bf16_f32 v60, v63, v220
	ds_write2_b32 v168, v60, v62 offset0:72 offset1:140
	v_fma_f32 v60, -v125, v220, v215
	v_fma_f32 v61, v125, v63, v219
	v_fmac_f32_e32 v60, v122, v63
	v_fmac_f32_e32 v61, v122, v220
	v_fma_f32 v63, -v125, v61, v214
	v_fmac_f32_e32 v218, v125, v60
	v_fmac_f32_e32 v63, v122, v60
	v_fmac_f32_e32 v218, v122, v61
	v_cvt_pk_bf16_f32 v62, v60, v61
	v_cvt_pk_bf16_f32 v60, v63, v218
	ds_write2_b32 v169, v60, v62 offset0:64 offset1:132
	v_mov_b32_e32 v132, v63
	v_mov_b32_e32 v133, v218
	v_mfma_f32_16x16x32_bf16 v[214:217], v[48:51], v[178:181], 0
	v_mfma_f32_16x16x32_bf16 v[222:225], v[48:51], v[186:189], 0
	v_mfma_f32_16x16x32_bf16 v[230:233], v[48:51], v[194:197], 0
	v_mfma_f32_16x16x32_bf16 v[238:241], v[48:51], v[202:205], 0
	v_mfma_f32_16x16x32_bf16 v[218:221], v[48:51], v[182:185], 0
	v_mfma_f32_16x16x32_bf16 v[226:229], v[48:51], v[190:193], 0
	v_mfma_f32_16x16x32_bf16 v[234:237], v[48:51], v[198:201], 0
	v_mfma_f32_16x16x32_bf16 v[242:245], v[48:51], v[206:209], 0
	v_cvt_pk_bf16_f32 v56, v56, v57
	v_cvt_pk_bf16_f32 v57, v58, v59
	v_lshl_add_u64 v[62:63], s[98:99], 0, v[248:249]
	global_store_dwordx2 v[62:63], v[56:57], off
	v_permlane32_swap_b32_e32 v214, v230
	v_permlane32_swap_b32_e32 v222, v238
	v_permlane32_swap_b32_e32 v215, v231
	v_permlane32_swap_b32_e32 v223, v239
	v_permlane32_swap_b32_e32 v216, v232
	v_permlane32_swap_b32_e32 v224, v240
	v_permlane32_swap_b32_e32 v217, v233
	v_permlane32_swap_b32_e32 v225, v241
	v_permlane16_swap_b32_e32 v214, v222
	v_permlane16_swap_b32_e32 v230, v238
	v_permlane16_swap_b32_e32 v215, v223
	v_permlane16_swap_b32_e32 v231, v239
	v_permlane16_swap_b32_e32 v216, v224
	v_permlane16_swap_b32_e32 v232, v240
	v_permlane16_swap_b32_e32 v217, v225
	v_permlane16_swap_b32_e32 v233, v241
	v_permlane32_swap_b32_e32 v218, v234
	v_permlane32_swap_b32_e32 v226, v242
	v_permlane32_swap_b32_e32 v219, v235
	v_permlane32_swap_b32_e32 v227, v243
	v_permlane32_swap_b32_e32 v220, v236
	v_permlane32_swap_b32_e32 v228, v244
	v_permlane32_swap_b32_e32 v221, v237
	v_permlane32_swap_b32_e32 v229, v245
	v_permlane16_swap_b32_e32 v218, v226
	v_permlane16_swap_b32_e32 v234, v242
	v_permlane16_swap_b32_e32 v219, v227
	v_permlane16_swap_b32_e32 v235, v243
	v_permlane16_swap_b32_e32 v220, v228
	v_permlane16_swap_b32_e32 v236, v244
	v_permlane16_swap_b32_e32 v221, v229
	v_permlane16_swap_b32_e32 v237, v245
	s_waitcnt vmcnt(1)
	v_mov_b32_e32 v48, v52
	v_mov_b32_e32 v49, v53
	v_mov_b32_e32 v50, v54
	v_mov_b32_e32 v51, v55
	v_lshl_add_u64 v[62:63], s[98:99], 0, v[246:247]
	global_load_dwordx4 v[52:55], v[62:63], off
	s_sub_u32 s98, s98, 0x8000
	s_subb_u32 s99, s99, 0
	s_add_i32 s100, s100, 1
	s_cmp_lg_u32 s100, 0x10d
	s_cbranch_scc1 .Ls5f_bwd_loop
	s_waitcnt vmcnt(0)
	s_mov_b32 s25, 0x10d
	s_add_u32 s0, s58, 48
	s_addc_u32 s1, s59, 0
	s_branch .LBB0_414

; #define LAS __attribute__((address_space(3)))
; DI unsigned pk2(float lo, float hi) { f32x2 v = {lo, hi}; bf16x2_t b = __builtin_convertvector(v, bf16x2_t); return __builtin_bit_cast(unsigned, b); }
; #define MFMA16(a, b, c) __builtin_amdgcn_mfma_f32_16x16x32_bf16((a), (b), (c), 0, 0, 0)
; #define S5_CB() asm volatile("" ::: "memory")
; DI void s5_phase(const KArgs& a, int zz, int o, const bf16_t* H, bf16_t* YF, bf16_t* YB, LAS unsigned char* lds, int G, int bid, int wave, int lane) {
;     ...
;         auto iter = [&](const int ci, const bool do_c) __attribute__((always_inline)) {
;             const size_t row0 = chunk_row(ci);
;             const u32x4 u3 = loadu(ci + 3);
;             f32x2 bu[16];
; #pragma unroll
;             for (int s = 0; s < 16; ++s) { const int tt = DIRC ? 15 - s : s; bu[s] = *(const LAS f32x2*)(BU + tt * 132 + 2 * lane); }
;             bf16x8 Ax[4];
;             if (do_c) {
; #pragma unroll
;                 for (int kb = 0; kb < 4; ++kb) Ax[kb] = *(const LAS bf16x8*)(XS + fr * 68 + kb * 16 + fq * 4); }
;             S5_CB();
;             stageA(u1);
;             S5_CB();
; #pragma unroll
;             for (int s = 0; s < 16; ++s) { const int tt = DIRC ? 15 - s : s;
;                 const float nr = __builtin_fmaf(abr, xr, __builtin_fmaf(nabi, xi, bu[s][0])); const float ni = __builtin_fmaf(abr, xi, __builtin_fmaf(abi, xr, bu[s][1])); xr = nr; xi = ni;
;                 XS[tt * 68 + lane] = pk2(xr, xi); }
;             if (do_c) {
;                 f32x4 ya = (f32x4){0.f, 0.f, 0.f, 0.f};
; #pragma unroll
;                 for (int kb = 0; kb < 4; ++kb) ya = MFMA16(Cb[kb], Ax[kb], ya);
;                 u32x2 w; w.x = pk2(ya[0], ya[1]); w.y = pk2(ya[2], ya[3]); *(u32x2*)(Y + (rowprev + fr) * D + g * 16 + fq * 4) = w; }
;             S5_CB();
;             rowprev = row0; u1 = u2; u2 = u3;
;         };
;         iter(0, false);
;         for (int ci = 1; ci < 272; ++ci) iter(ci, true);
.LBB0_417:
	s_waitcnt vmcnt(1)
	s_cmp_lt_u32 s23, 16
	s_cselect_b64 s[26:27], -1, 0
	s_add_i32 s25, s24, 0xfffeff00
	s_and_b64 s[26:27], s[26:27], exec
	s_cselect_b32 s25, s24, s25
	s_cselect_b32 s26, s54, s56
	s_cselect_b32 s27, s55, s57
	s_add_u32 s26, s26, s25
	s_addc_u32 s27, s27, 0
	s_min_i32 s25, s23, 0x10c
	s_cmp_lt_u32 s23, 13
	s_cselect_b64 s[30:31], -1, 0
	s_lshl_b32 s25, s25, 4
	s_and_b64 s[30:31], s[30:31], exec
	s_movk_i32 s30, 0xff30
	s_cselect_b32 s30, 0x10030, s30
	s_cselect_b32 s31, s55, s57
	s_cselect_b32 s34, s54, s56
	s_add_i32 s25, s25, s30
	s_add_u32 s25, s34, s25
	s_addc_u32 s30, s31, 0
	v_cndmask_b32_e64 v170, 0, v53, s[38:39]
	v_cndmask_b32_e64 v171, 0, v52, s[38:39]
	v_mov_b32_e32 v53, s30
	v_or_b32_e32 v52, s25, v104
	v_lshlrev_b64 v[52:53], 11, v[52:53]
	v_lshl_add_u64 v[52:53], v[126:127], 0, v[52:53]
	v_add_u32_e32 v132, v134, v107
	v_cndmask_b32_e64 v133, 0, v55, s[38:39]
	v_cndmask_b32_e64 v148, 0, v54, s[38:39]
	global_load_dwordx4 v[52:55], v[52:53], off
	ds_read_b128 v[56:59], v132 offset:8448
	ds_read_b128 v[60:63], v132 offset:8512
	ds_read_b128 v[64:67], v132 offset:8576
	ds_read_b128 v[68:71], v132 offset:8640
	s_waitcnt lgkmcnt(0)
	v_mfma_f32_16x16x32_bf16 v[56:59], v[32:35], v[56:59], 0
	v_mfma_f32_16x16x32_bf16 v[56:59], v[36:39], v[60:63], v[56:59]
	v_mfma_f32_16x16x32_bf16 v[56:59], v[40:43], v[64:67], v[56:59]
	v_mfma_f32_16x16x32_bf16 v[56:59], v[44:47], v[68:71], v[56:59]
	v_fma_f32 v60, -v125, v131, v214
	v_fma_f32 v61, v125, v130, v218
	v_fmac_f32_e32 v60, v122, v130
	v_fmac_f32_e32 v61, v122, v131
	v_fma_f32 v63, -v125, v61, v215
	v_fmac_f32_e32 v219, v125, v60
	v_fmac_f32_e32 v63, v122, v60
	v_fmac_f32_e32 v219, v122, v61
	v_cvt_pk_bf16_f32 v62, v60, v61
	v_cvt_pk_bf16_f32 v60, v63, v219
	ds_write2_b32 v169, v62, v60 offset0:64 offset1:132
	v_fma_f32 v60, -v125, v219, v216
	v_fma_f32 v61, v125, v63, v220
	v_fmac_f32_e32 v60, v122, v63
	v_fmac_f32_e32 v61, v122, v219
	v_fma_f32 v63, -v125, v61, v217
	v_fmac_f32_e32 v221, v125, v60
	v_fmac_f32_e32 v63, v122, v60
	v_fmac_f32_e32 v221, v122, v61
	v_cvt_pk_bf16_f32 v62, v60, v61
	v_cvt_pk_bf16_f32 v60, v63, v221
	ds_write2_b32 v168, v62, v60 offset0:72 offset1:140
	v_fma_f32 v60, -v125, v221, v222
	v_fma_f32 v61, v125, v63, v226
	v_fmac_f32_e32 v60, v122, v63
	v_fmac_f32_e32 v61, v122, v221
	v_fma_f32 v63, -v125, v61, v223
	v_fmac_f32_e32 v227, v125, v60
	v_fmac_f32_e32 v63, v122, v60
	v_fmac_f32_e32 v227, v122, v61
	v_cvt_pk_bf16_f32 v62, v60, v61
	v_cvt_pk_bf16_f32 v60, v63, v227
	ds_write2_b32 v167, v62, v60 offset0:80 offset1:148
	v_fma_f32 v60, -v125, v227, v224
	v_fma_f32 v61, v125, v63, v228
	v_fmac_f32_e32 v60, v122, v63
	v_fmac_f32_e32 v61, v122, v227
	v_fma_f32 v63, -v125, v61, v225
	v_fmac_f32_e32 v229, v125, v60
	v_fmac_f32_e32 v63, v122, v60
	v_fmac_f32_e32 v229, v122, v61
	v_cvt_pk_bf16_f32 v62, v60, v61
	v_cvt_pk_bf16_f32 v60, v63, v229
	ds_write2_b32 v166, v62, v60 offset0:88 offset1:156
	v_fma_f32 v60, -v125, v229, v230
	v_fma_f32 v61, v125, v63, v234
	v_fmac_f32_e32 v60, v122, v63
	v_fmac_f32_e32 v61, v122, v229
	v_fma_f32 v63, -v125, v61, v231
	v_fmac_f32_e32 v235, v125, v60
	v_fmac_f32_e32 v63, v122, v60
	v_fmac_f32_e32 v235, v122, v61
	v_cvt_pk_bf16_f32 v62, v60, v61
	v_cvt_pk_bf16_f32 v60, v63, v235
	ds_write2_b32 v165, v62, v60 offset0:96 offset1:164
	v_fma_f32 v60, -v125, v235, v232
	v_fma_f32 v61, v125, v63, v236
	v_fmac_f32_e32 v60, v122, v63
	v_fmac_f32_e32 v61, v122, v235
	v_fma_f32 v63, -v125, v61, v233
	v_fmac_f32_e32 v237, v125, v60
	v_fmac_f32_e32 v63, v122, v60
	v_fmac_f32_e32 v237, v122, v61
	v_cvt_pk_bf16_f32 v62, v60, v61
	v_cvt_pk_bf16_f32 v60, v63, v237
	ds_write2_b32 v164, v62, v60 offset0:104 offset1:172
	v_fma_f32 v60, -v125, v237, v238
	v_fma_f32 v61, v125, v63, v242
	v_fmac_f32_e32 v60, v122, v63
	v_fmac_f32_e32 v61, v122, v237
	v_fma_f32 v63, -v125, v61, v239
	v_fmac_f32_e32 v243, v125, v60
	v_fmac_f32_e32 v63, v122, v60
	v_fmac_f32_e32 v243, v122, v61
	v_cvt_pk_bf16_f32 v62, v60, v61
	v_cvt_pk_bf16_f32 v60, v63, v243
	ds_write2_b32 v163, v62, v60 offset0:112 offset1:180
	v_fma_f32 v60, -v125, v243, v240
	v_fma_f32 v61, v125, v63, v244
	v_fmac_f32_e32 v60, v122, v63
	v_fmac_f32_e32 v61, v122, v243
	v_fma_f32 v63, -v125, v61, v241
	v_fmac_f32_e32 v245, v125, v60
	v_fmac_f32_e32 v63, v122, v60
	v_fmac_f32_e32 v245, v122, v61
	v_cvt_pk_bf16_f32 v62, v60, v61
	v_cvt_pk_bf16_f32 v60, v63, v245
	ds_write2_b32 v162, v62, v60 offset0:120 offset1:188
	v_mov_b32_e32 v130, v63
	v_mov_b32_e32 v131, v245
	v_mfma_f32_16x16x32_bf16 v[214:217], v[48:51], v[178:181], 0
	v_mfma_f32_16x16x32_bf16 v[222:225], v[48:51], v[186:189], 0
	v_mfma_f32_16x16x32_bf16 v[230:233], v[48:51], v[194:197], 0
	v_mfma_f32_16x16x32_bf16 v[238:241], v[48:51], v[202:205], 0
	v_mfma_f32_16x16x32_bf16 v[218:221], v[48:51], v[182:185], 0
	v_mfma_f32_16x16x32_bf16 v[226:229], v[48:51], v[190:193], 0
	v_mfma_f32_16x16x32_bf16 v[234:237], v[48:51], v[198:201], 0
	v_mfma_f32_16x16x32_bf16 v[242:245], v[48:51], v[206:209], 0
	v_cvt_pk_bf16_f32 v56, v56, v57
	v_cvt_pk_bf16_f32 v57, v58, v59
	v_lshl_add_u64 v[62:63], s[0:1], 0, v[104:105]
	v_lshlrev_b64 v[62:63], 11, v[62:63]
	v_lshl_add_u64 v[62:63], v[128:129], 0, v[62:63]
	global_store_dwordx2 v[62:63], v[56:57], off
	v_permlane32_swap_b32_e32 v214, v230
	v_permlane32_swap_b32_e32 v222, v238
	v_permlane32_swap_b32_e32 v215, v231
	v_permlane32_swap_b32_e32 v223, v239
	v_permlane32_swap_b32_e32 v216, v232
	v_permlane32_swap_b32_e32 v224, v240
	v_permlane32_swap_b32_e32 v217, v233
	v_permlane32_swap_b32_e32 v225, v241
	v_permlane16_swap_b32_e32 v214, v222
	v_permlane16_swap_b32_e32 v230, v238
	v_permlane16_swap_b32_e32 v215, v223
	v_permlane16_swap_b32_e32 v231, v239
	v_permlane16_swap_b32_e32 v216, v224
	v_permlane16_swap_b32_e32 v232, v240
	v_permlane16_swap_b32_e32 v217, v225
	v_permlane16_swap_b32_e32 v233, v241
	v_permlane32_swap_b32_e32 v218, v234
	v_permlane32_swap_b32_e32 v226, v242
	v_permlane32_swap_b32_e32 v219, v235
	v_permlane32_swap_b32_e32 v227, v243
	v_permlane32_swap_b32_e32 v220, v236
	v_permlane32_swap_b32_e32 v228, v244
	v_permlane32_swap_b32_e32 v221, v237
	v_permlane32_swap_b32_e32 v229, v245
	v_permlane16_swap_b32_e32 v218, v226
	v_permlane16_swap_b32_e32 v234, v242
	v_permlane16_swap_b32_e32 v219, v227
	v_permlane16_swap_b32_e32 v235, v243
	v_permlane16_swap_b32_e32 v220, v228
	v_permlane16_swap_b32_e32 v236, v244
	v_permlane16_swap_b32_e32 v221, v229
	v_permlane16_swap_b32_e32 v237, v245
	s_mov_b64 s[0:1], s[26:27]
	v_mov_b32_e32 v48, v171
	v_mov_b32_e32 v49, v170
	v_mov_b32_e32 v50, v148
	v_mov_b32_e32 v51, v133
	s_add_i32 s23, s23, 1
	s_add_i32 s24, s24, 16
	s_cmp_eq_u32 s23, 17
	s_cbranch_scc1 .Ls5f_fwd_entry
; #define LAS __attribute__((address_space(3)))
; DI unsigned pk2(float lo, float hi) { f32x2 v = {lo, hi}; bf16x2_t b = __builtin_convertvector(v, bf16x2_t); return __builtin_bit_cast(unsigned, b); }
; #define LDS_WAIT() asm volatile("s_waitcnt lgkmcnt(0)" ::: "memory")
; #define MFMA16(a, b, c) __builtin_amdgcn_mfma_f32_16x16x32_bf16((a), (b), (c), 0, 0, 0)
; DI void s5_phase(const KArgs& a, int zz, int o, const bf16_t* H, bf16_t* YF, bf16_t* YB, LAS unsigned char* lds, int G, int bid, int wave, int lane) {
;     ...
;         for (int ci = 1; ci < 272; ++ci) iter(ci, true);
;         {
;             f32x4 ya = (f32x4){0.f, 0.f, 0.f, 0.f};
; #pragma unroll
;             for (int kb = 0; kb < 4; ++kb) { const bf16x8 Ax = *(const LAS bf16x8*)(XS + fr * 68 + kb * 16 + fq * 4); ya = MFMA16(Cb[kb], Ax, ya); }
;             u32x2 w; w.x = pk2(ya[0], ya[1]); w.y = pk2(ya[2], ya[3]); *(u32x2*)(Y + (rowprev + fr) * D + g * 16 + fq * 4) = w;
;         }
;         LDS_WAIT();
;         };
;         if (dir) run_dir(std::true_type{}); else run_dir(std::false_type{});
	s_cmp_lg_u32 s24, 0x11100
	s_cbranch_scc1 .LBB0_417
	s_waitcnt vmcnt(0)
	ds_read_b128 v[0:3], v132 offset:8448
	ds_read_b128 v[4:7], v132 offset:8512
	v_lshlrev_b32_e32 v148, 1, v106
	s_waitcnt lgkmcnt(1)
	v_mfma_f32_16x16x32_bf16 v[0:3], v[32:35], v[0:3], 0
	s_waitcnt lgkmcnt(0)
	v_mfma_f32_16x16x32_bf16 v[0:3], v[36:39], v[4:7], v[0:3]
	ds_read_b128 v[4:7], v132 offset:8576
	s_waitcnt lgkmcnt(0)
	v_mfma_f32_16x16x32_bf16 v[0:3], v[40:43], v[4:7], v[0:3]
	ds_read_b128 v[4:7], v132 offset:8640
	s_waitcnt lgkmcnt(0)
	v_mfma_f32_16x16x32_bf16 v[0:3], v[44:47], v[4:7], v[0:3]
	s_nop 7
	v_cvt_pk_bf16_f32 v0, v0, v1
	v_cvt_pk_bf16_f32 v1, v2, v3
	v_mov_b32_e32 v3, s27
	v_or_b32_e32 v2, s26, v104
	v_lshlrev_b64 v[2:3], 11, v[2:3]
	v_lshl_add_u64 v[2:3], s[4:5], 0, v[2:3]
	v_lshl_add_u64 v[2:3], s[52:53], 1, v[2:3]
	v_lshl_add_u64 v[2:3], v[2:3], 0, v[148:149]
	global_store_dwordx2 v[2:3], v[0:1], off
	s_waitcnt lgkmcnt(0)
	s_branch .LBB0_394
.Ls5f_fwd_entry:
	s_add_u32 s98, s56, 64
	s_addc_u32 s99, s57, 0
	s_mov_b32 s100, 0xfffe0000
	s_mov_b32 s101, -1
	s_lshl_b64 s[98:99], s[98:99], 11
	v_lshlrev_b64 v[56:57], 11, v[104:105]
	v_lshl_add_u64 v[246:247], v[126:127], 0, v[56:57]
	v_lshl_add_u64 v[248:249], v[128:129], 0, v[56:57]
	v_lshl_add_u64 v[248:249], v[248:249], 0, s[100:101]
	s_mov_b32 s100, 17
; #define LAS __attribute__((address_space(3)))
; DI unsigned pk2(float lo, float hi) { f32x2 v = {lo, hi}; bf16x2_t b = __builtin_convertvector(v, bf16x2_t); return __builtin_bit_cast(unsigned, b); }
; #define MFMA16(a, b, c) __builtin_amdgcn_mfma_f32_16x16x32_bf16((a), (b), (c), 0, 0, 0)
; #define S5_CB() asm volatile("" ::: "memory")
; DI void s5_phase(const KArgs& a, int zz, int o, const bf16_t* H, bf16_t* YF, bf16_t* YB, LAS unsigned char* lds, int G, int bid, int wave, int lane) {
;     ...
;         auto iter = [&](const int ci, const bool do_c) __attribute__((always_inline)) {
;             const size_t row0 = chunk_row(ci);
;             const u32x4 u3 = loadu(ci + 3);
;             f32x2 bu[16];
; #pragma unroll
;             for (int s = 0; s < 16; ++s) { const int tt = DIRC ? 15 - s : s; bu[s] = *(const LAS f32x2*)(BU + tt * 132 + 2 * lane); }
;             bf16x8 Ax[4];
;             if (do_c) {
; #pragma unroll
;                 for (int kb = 0; kb < 4; ++kb) Ax[kb] = *(const LAS bf16x8*)(XS + fr * 68 + kb * 16 + fq * 4); }
;             S5_CB();
;             stageA(u1);
;             S5_CB();
; #pragma unroll
;             for (int s = 0; s < 16; ++s) { const int tt = DIRC ? 15 - s : s;
;                 const float nr = __builtin_fmaf(abr, xr, __builtin_fmaf(nabi, xi, bu[s][0])); const float ni = __builtin_fmaf(abr, xi, __builtin_fmaf(abi, xr, bu[s][1])); xr = nr; xi = ni;
;                 XS[tt * 68 + lane] = pk2(xr, xi); }
;             if (do_c) {
;                 f32x4 ya = (f32x4){0.f, 0.f, 0.f, 0.f};
; #pragma unroll
;                 for (int kb = 0; kb < 4; ++kb) ya = MFMA16(Cb[kb], Ax[kb], ya);
;                 u32x2 w; w.x = pk2(ya[0], ya[1]); w.y = pk2(ya[2], ya[3]); *(u32x2*)(Y + (rowprev + fr) * D + g * 16 + fq * 4) = w; }
;             S5_CB();
;             rowprev = row0; u1 = u2; u2 = u3;
;         };
;         iter(0, false);
;         for (int ci = 1; ci < 272; ++ci) iter(ci, true);
.Ls5f_fwd_loop:
	ds_read_b128 v[56:59], v132 offset:8448
	ds_read_b128 v[60:63], v132 offset:8512
	ds_read_b128 v[64:67], v132 offset:8576
	ds_read_b128 v[68:71], v132 offset:8640
	s_waitcnt lgkmcnt(0)
	v_mfma_f32_16x16x32_bf16 v[56:59], v[32:35], v[56:59], 0
	v_mfma_f32_16x16x32_bf16 v[56:59], v[36:39], v[60:63], v[56:59]
	v_mfma_f32_16x16x32_bf16 v[56:59], v[40:43], v[64:67], v[56:59]
	v_mfma_f32_16x16x32_bf16 v[56:59], v[44:47], v[68:71], v[56:59]
	v_fma_f32 v60, -v125, v131, v214
	v_fma_f32 v61, v125, v130, v218
	v_fmac_f32_e32 v60, v122, v130
	v_fmac_f32_e32 v61, v122, v131
	v_fma_f32 v63, -v125, v61, v215
	v_fmac_f32_e32 v219, v125, v60
	v_fmac_f32_e32 v63, v122, v60
	v_fmac_f32_e32 v219, v122, v61
	v_cvt_pk_bf16_f32 v62, v60, v61
	v_cvt_pk_bf16_f32 v60, v63, v219
	ds_write2_b32 v169, v62, v60 offset0:64 offset1:132
	v_fma_f32 v60, -v125, v219, v216
	v_fma_f32 v61, v125, v63, v220
	v_fmac_f32_e32 v60, v122, v63
	v_fmac_f32_e32 v61, v122, v219
	v_fma_f32 v63, -v125, v61, v217
	v_fmac_f32_e32 v221, v125, v60
	v_fmac_f32_e32 v63, v122, v60
	v_fmac_f32_e32 v221, v122, v61
	v_cvt_pk_bf16_f32 v62, v60, v61
	v_cvt_pk_bf16_f32 v60, v63, v221
	ds_write2_b32 v168, v62, v60 offset0:72 offset1:140
	v_fma_f32 v60, -v125, v221, v222
	v_fma_f32 v61, v125, v63, v226
	v_fmac_f32_e32 v60, v122, v63
	v_fmac_f32_e32 v61, v122, v221
	v_fma_f32 v63, -v125, v61, v223
	v_fmac_f32_e32 v227, v125, v60
	v_fmac_f32_e32 v63, v122, v60
	v_fmac_f32_e32 v227, v122, v61
	v_cvt_pk_bf16_f32 v62, v60, v61
	v_cvt_pk_bf16_f32 v60, v63, v227
	ds_write2_b32 v167, v62, v60 offset0:80 offset1:148
	v_fma_f32 v60, -v125, v227, v224
	v_fma_f32 v61, v125, v63, v228
	v_fmac_f32_e32 v60, v122, v63
	v_fmac_f32_e32 v61, v122, v227
	v_fma_f32 v63, -v125, v61, v225
	v_fmac_f32_e32 v229, v125, v60
	v_fmac_f32_e32 v63, v122, v60
	v_fmac_f32_e32 v229, v122, v61
	v_cvt_pk_bf16_f32 v62, v60, v61
	v_cvt_pk_bf16_f32 v60, v63, v229
	ds_write2_b32 v166, v62, v60 offset0:88 offset1:156
	v_fma_f32 v60, -v125, v229, v230
	v_fma_f32 v61, v125, v63, v234
	v_fmac_f32_e32 v60, v122, v63
	v_fmac_f32_e32 v61, v122, v229
	v_fma_f32 v63, -v125, v61, v231
	v_fmac_f32_e32 v235, v125, v60
	v_fmac_f32_e32 v63, v122, v60
	v_fmac_f32_e32 v235, v122, v61
	v_cvt_pk_bf16_f32 v62, v60, v61
	v_cvt_pk_bf16_f32 v60, v63, v235
	ds_write2_b32 v165, v62, v60 offset0:96 offset1:164
	v_fma_f32 v60, -v125, v235, v232
	v_fma_f32 v61, v125, v63, v236
	v_fmac_f32_e32 v60, v122, v63
	v_fmac_f32_e32 v61, v122, v235
	v_fma_f32 v63, -v125, v61, v233
	v_fmac_f32_e32 v237, v125, v60
	v_fmac_f32_e32 v63, v122, v60
	v_fmac_f32_e32 v237, v122, v61
	v_cvt_pk_bf16_f32 v62, v60, v61
	v_cvt_pk_bf16_f32 v60, v63, v237
	ds_write2_b32 v164, v62, v60 offset0:104 offset1:172
	v_fma_f32 v60, -v125, v237, v238
	v_fma_f32 v61, v125, v63, v242
	v_fmac_f32_e32 v60, v122, v63
	v_fmac_f32_e32 v61, v122, v237
	v_fma_f32 v63, -v125, v61, v239
	v_fmac_f32_e32 v243, v125, v60
	v_fmac_f32_e32 v63, v122, v60
	v_fmac_f32_e32 v243, v122, v61
	v_cvt_pk_bf16_f32 v62, v60, v61
	v_cvt_pk_bf16_f32 v60, v63, v243
	ds_write2_b32 v163, v62, v60 offset0:112 offset1:180
	v_fma_f32 v60, -v125, v243, v240
	v_fma_f32 v61, v125, v63, v244
	v_fmac_f32_e32 v60, v122, v63
	v_fmac_f32_e32 v61, v122, v243
	v_fma_f32 v63, -v125, v61, v241
	v_fmac_f32_e32 v245, v125, v60
	v_fmac_f32_e32 v63, v122, v60
	v_fmac_f32_e32 v245, v122, v61
	v_cvt_pk_bf16_f32 v62, v60, v61
	v_cvt_pk_bf16_f32 v60, v63, v245
	ds_write2_b32 v162, v62, v60 offset0:120 offset1:188
	v_mov_b32_e32 v130, v63
	v_mov_b32_e32 v131, v245
	v_mfma_f32_16x16x32_bf16 v[214:217], v[48:51], v[178:181], 0
	v_mfma_f32_16x16x32_bf16 v[222:225], v[48:51], v[186:189], 0
	v_mfma_f32_16x16x32_bf16 v[230:233], v[48:51], v[194:197], 0
	v_mfma_f32_16x16x32_bf16 v[238:241], v[48:51], v[202:205], 0
	v_mfma_f32_16x16x32_bf16 v[218:221], v[48:51], v[182:185], 0
	v_mfma_f32_16x16x32_bf16 v[226:229], v[48:51], v[190:193], 0
	v_mfma_f32_16x16x32_bf16 v[234:237], v[48:51], v[198:201], 0
	v_mfma_f32_16x16x32_bf16 v[242:245], v[48:51], v[206:209], 0
	v_cvt_pk_bf16_f32 v56, v56, v57
	v_cvt_pk_bf16_f32 v57, v58, v59
	v_lshl_add_u64 v[62:63], s[98:99], 0, v[248:249]
	global_store_dwordx2 v[62:63], v[56:57], off
	v_permlane32_swap_b32_e32 v214, v230
	v_permlane32_swap_b32_e32 v222, v238
	v_permlane32_swap_b32_e32 v215, v231
	v_permlane32_swap_b32_e32 v223, v239
	v_permlane32_swap_b32_e32 v216, v232
	v_permlane32_swap_b32_e32 v224, v240
	v_permlane32_swap_b32_e32 v217, v233
	v_permlane32_swap_b32_e32 v225, v241
	v_permlane16_swap_b32_e32 v214, v222
	v_permlane16_swap_b32_e32 v230, v238
	v_permlane16_swap_b32_e32 v215, v223
	v_permlane16_swap_b32_e32 v231, v239
	v_permlane16_swap_b32_e32 v216, v224
	v_permlane16_swap_b32_e32 v232, v240
	v_permlane16_swap_b32_e32 v217, v225
	v_permlane16_swap_b32_e32 v233, v241
	v_permlane32_swap_b32_e32 v218, v234
	v_permlane32_swap_b32_e32 v226, v242
	v_permlane32_swap_b32_e32 v219, v235
	v_permlane32_swap_b32_e32 v227, v243
	v_permlane32_swap_b32_e32 v220, v236
	v_permlane32_swap_b32_e32 v228, v244
	v_permlane32_swap_b32_e32 v221, v237
	v_permlane32_swap_b32_e32 v229, v245
	v_permlane16_swap_b32_e32 v218, v226
	v_permlane16_swap_b32_e32 v234, v242
	v_permlane16_swap_b32_e32 v219, v227
	v_permlane16_swap_b32_e32 v235, v243
	v_permlane16_swap_b32_e32 v220, v228
	v_permlane16_swap_b32_e32 v236, v244
	v_permlane16_swap_b32_e32 v221, v229
	v_permlane16_swap_b32_e32 v237, v245
	s_waitcnt vmcnt(1)
	v_mov_b32_e32 v48, v52
	v_mov_b32_e32 v49, v53
	v_mov_b32_e32 v50, v54
	v_mov_b32_e32 v51, v55
	v_lshl_add_u64 v[62:63], s[98:99], 0, v[246:247]
	global_load_dwordx4 v[52:55], v[62:63], off
	s_add_u32 s98, s98, 0x8000
	s_addc_u32 s99, s99, 0
	s_add_i32 s100, s100, 1
	s_cmp_lg_u32 s100, 0x10d
	s_cbranch_scc1 .Ls5f_fwd_loop
	s_waitcnt vmcnt(0)
	s_mov_b32 s23, 0x10d
	s_mov_b32 s24, 0x110d0
	s_add_u32 s0, s56, 0xfc0
	s_addc_u32 s1, s57, 0
	s_branch .LBB0_417
